# nt (streaming) policy on the P2 and P9 GEMM output stores
# baseline (speedup 1.0000x reference)
; template <bool BF> __device__ __forceinline__ unsigned pk2(float lo, float hi) { return BF ? pk_bf2(lo, hi) : pk_h2(lo, hi); }
;     __device__ __forceinline__ void operator()(const f32x4 (&acc)[2][2][4][2], const Unit& u, int wr, int wc, int fr, int fq) const {
;         const int row0 = u.pm * BM + wr * 64 + fr; const int col0 = u.pn * BM + wc * 32 + 8 * fq;
; #pragma unroll
;         for (int ai = 0; ai < 2; ++ai)
; #pragma unroll
;             for (int m = 0; m < 4; ++m) { h16* rowp = O + (size_t)(row0 + ai * HALF + m * 16) * ldc + col0;
; #pragma unroll
;                 for (int bj = 0; bj < 2; ++bj) { f32x4 v0 = acc[ai][bj][m][0], v1 = acc[ai][bj][m][1];
;                     if (ACT == 1) {
; #pragma unroll
;                         for (int j = 0; j < 4; ++j) { const float a = fmaxf(v0[j], 0.f), b = fmaxf(v1[j], 0.f); v0[j] = a * a; v1[j] = b * b; } }
;                     u32x4 w; w.x = pk2<BF>(v0[0], v0[1]); w.y = pk2<BF>(v0[2], v0[3]); w.z = pk2<BF>(v1[0], v1[1]); w.w = pk2<BF>(v1[2], v1[3]);
;                     *(u32x4*)(rowp + bj * HALF) = w; } }
.LBB0_270:
	v_lshl_add_u32 v158, s18, 8, v146
	v_lshl_or_b32 v152, s49, 8, v148
	v_ashrrev_i32_e32 v153, 31, v152
	v_mov_b64_e32 v[154:155], s[8:9]
	v_cvt_pk_f16_f32 v70, v70, v71
	v_cvt_pk_f16_f32 v71, v72, v73
	v_cvt_pk_f16_f32 v72, v66, v67
	v_add_u32_e32 v66, 0x80, v158
	v_mad_i64_i32 v[156:157], s[34:35], v158, s48, v[154:155]
	v_lshlrev_b64 v[152:153], 1, v[152:153]
	v_cvt_pk_f16_f32 v110, v110, v111
	v_cvt_pk_f16_f32 v111, v112, v113
	v_cvt_pk_f16_f32 v112, v106, v107
	v_or_b32_e32 v106, 16, v158
	v_mad_i64_i32 v[66:67], s[34:35], v66, s48, v[154:155]
	v_cvt_pk_f16_f32 v46, v46, v47
	v_cvt_pk_f16_f32 v47, v48, v49
	v_cvt_pk_f16_f32 v48, v42, v43
	v_add_u32_e32 v42, 0x90, v158
	v_lshl_add_u64 v[156:157], v[156:157], 0, v[152:153]
	v_cvt_pk_f16_f32 v113, v108, v109
	v_mad_i64_i32 v[106:107], s[34:35], v106, s48, v[154:155]
	v_cvt_pk_f16_f32 v94, v94, v95
	v_cvt_pk_f16_f32 v95, v96, v97
	v_cvt_pk_f16_f32 v96, v90, v91
	v_or_b32_e32 v90, 32, v158
	v_lshl_add_u64 v[66:67], v[66:67], 0, v[152:153]
	v_cvt_pk_f16_f32 v49, v44, v45
	v_mad_i64_i32 v[42:43], s[34:35], v42, s48, v[154:155]
	v_cvt_pk_f16_f32 v30, v30, v31
	v_cvt_pk_f16_f32 v31, v32, v33
	v_cvt_pk_f16_f32 v32, v26, v27
	v_add_u32_e32 v26, 0xa0, v158
	global_store_dwordx4 v[156:157], v[110:113], off offset:256 nt
	v_cvt_pk_f16_f32 v97, v92, v93
	v_mad_i64_i32 v[90:91], s[34:35], v90, s48, v[154:155]
	v_lshl_add_u64 v[110:111], v[106:107], 0, v[152:153]
	v_cvt_pk_f16_f32 v78, v78, v79
	v_cvt_pk_f16_f32 v79, v80, v81
	v_cvt_pk_f16_f32 v80, v74, v75
	v_or_b32_e32 v74, 48, v158
	global_store_dwordx4 v[66:67], v[46:49], off offset:256 nt
	v_cvt_pk_f16_f32 v33, v28, v29
	v_mad_i64_i32 v[26:27], s[34:35], v26, s48, v[154:155]
	v_lshl_add_u64 v[46:47], v[42:43], 0, v[152:153]
	v_cvt_pk_f16_f32 v14, v14, v15
	v_cvt_pk_f16_f32 v15, v16, v17
	v_cvt_pk_f16_f32 v16, v10, v11
	v_add_u32_e32 v10, 0xb0, v158
	global_store_dwordx4 v[110:111], v[94:97], off offset:256 nt
	v_cvt_pk_f16_f32 v81, v76, v77
	v_mad_i64_i32 v[74:75], s[34:35], v74, s48, v[154:155]
	v_lshl_add_u64 v[94:95], v[90:91], 0, v[152:153]
	global_store_dwordx4 v[46:47], v[30:33], off offset:256 nt
	v_cvt_pk_f16_f32 v17, v12, v13
	v_mad_i64_i32 v[10:11], s[34:35], v10, s48, v[154:155]
	v_lshl_add_u64 v[30:31], v[26:27], 0, v[152:153]
	v_cvt_pk_f16_f32 v126, v126, v127
	v_cvt_pk_f16_f32 v127, v128, v129
	v_cvt_pk_f16_f32 v128, v122, v123
	v_cvt_pk_f16_f32 v129, v124, v125
	v_cvt_pk_f16_f32 v106, v118, v119
	v_cvt_pk_f16_f32 v107, v120, v121
	v_cvt_pk_f16_f32 v108, v114, v115
	v_cvt_pk_f16_f32 v109, v116, v117
	v_cvt_pk_f16_f32 v90, v102, v103
	v_cvt_pk_f16_f32 v91, v104, v105
	v_cvt_pk_f16_f32 v92, v98, v99
	v_cvt_pk_f16_f32 v93, v100, v101
	global_store_dwordx4 v[94:95], v[78:81], off offset:256 nt
	v_cvt_pk_f16_f32 v76, v82, v83
	v_cvt_pk_f16_f32 v77, v84, v85
	v_lshl_add_u64 v[78:79], v[74:75], 0, v[152:153]
	v_cvt_pk_f16_f32 v74, v86, v87
	v_cvt_pk_f16_f32 v75, v88, v89
	v_cvt_pk_f16_f32 v73, v68, v69
	v_cvt_pk_f16_f32 v62, v62, v63
	v_cvt_pk_f16_f32 v63, v64, v65
	v_cvt_pk_f16_f32 v64, v58, v59
	v_cvt_pk_f16_f32 v65, v60, v61
	v_cvt_pk_f16_f32 v42, v54, v55
	v_cvt_pk_f16_f32 v43, v56, v57
	v_cvt_pk_f16_f32 v44, v50, v51
	v_cvt_pk_f16_f32 v45, v52, v53
	v_cvt_pk_f16_f32 v26, v38, v39
	v_cvt_pk_f16_f32 v27, v40, v41
	v_cvt_pk_f16_f32 v28, v34, v35
	v_cvt_pk_f16_f32 v29, v36, v37
	global_store_dwordx4 v[30:31], v[14:17], off offset:256 nt
	v_cvt_pk_f16_f32 v12, v18, v19
	v_cvt_pk_f16_f32 v13, v20, v21
	v_lshl_add_u64 v[14:15], v[10:11], 0, v[152:153]
	v_cvt_pk_f16_f32 v10, v22, v23
	v_cvt_pk_f16_f32 v11, v24, v25
	v_cvt_pk_f16_f32 v6, v6, v7
	v_cvt_pk_f16_f32 v7, v8, v9
	v_cvt_pk_f16_f32 v8, v2, v3
	v_cvt_pk_f16_f32 v9, v4, v5
	s_andn2_b64 vcc, exec, s[4:5]
	s_mov_b64 s[4:5], -1
	global_store_dwordx4 v[156:157], v[126:129], off nt
	global_store_dwordx4 v[110:111], v[106:109], off nt
	global_store_dwordx4 v[94:95], v[90:93], off nt
	global_store_dwordx4 v[78:79], v[74:77], off nt
	global_store_dwordx4 v[78:79], v[70:73], off offset:256 nt
	global_store_dwordx4 v[66:67], v[62:65], off nt
	global_store_dwordx4 v[46:47], v[42:45], off nt
	global_store_dwordx4 v[30:31], v[26:29], off nt
	global_store_dwordx4 v[14:15], v[10:13], off nt
	global_store_dwordx4 v[14:15], v[6:9], off offset:256 nt
	s_cbranch_vccnz .LBB0_263
	s_andn2_b64 vcc, exec, s[6:7]
	s_cbranch_vccnz .LBB0_262
	s_barrier
	s_branch .LBB0_262

; template <bool BF> __device__ __forceinline__ unsigned pk2(float lo, float hi) { return BF ? pk_bf2(lo, hi) : pk_h2(lo, hi); }
;     __device__ __forceinline__ void operator()(const f32x4 (&acc)[2][2][4][2], const Unit& u, int wr, int wc, int fr, int fq) const {
;     ...
;             for (int m = 0; m < 4; ++m) { h16* rowp = O + (size_t)(row0 + ai * HALF + m * 16) * ldc + col0;
; #pragma unroll
;                 for (int bj = 0; bj < 2; ++bj) { f32x4 v0 = acc[ai][bj][m][0], v1 = acc[ai][bj][m][1];
;                     if (ACT == 1) {
; #pragma unroll
;                         for (int j = 0; j < 4; ++j) { const float a = fmaxf(v0[j], 0.f), b = fmaxf(v1[j], 0.f); v0[j] = a * a; v1[j] = b * b; } }
;                     u32x4 w; w.x = pk2<BF>(v0[0], v0[1]); w.y = pk2<BF>(v0[2], v0[3]); w.z = pk2<BF>(v1[0], v1[1]); w.w = pk2<BF>(v1[2], v1[3]);
;                     *(u32x4*)(rowp + bj * HALF) = w; } }
.LBB0_872:
	v_lshl_add_u32 v154, s38, 8, v148
	v_ashrrev_i32_e32 v155, 31, v154
	v_max_f32_e32 v122, 0, v122
	v_lshl_or_b32 v146, s59, 8, v150
	v_lshlrev_b64 v[156:157], 14, v[154:155]
	v_mul_f32_e32 v155, v122, v122
	v_max_f32_e32 v123, 0, v123
	v_max_f32_e32 v124, 0, v124
	v_ashrrev_i32_e32 v147, 31, v146
	v_max_f32_e32 v122, 0, v127
	v_mul_f32_e32 v127, v123, v123
	v_max_f32_e32 v123, v128, v128
	v_mul_f32_e32 v128, v124, v124
	v_lshl_add_u64 v[156:157], s[8:9], 0, v[156:157]
	v_lshlrev_b64 v[158:159], 1, v[146:147]
	v_max_f32_e32 v126, 0, v126
	v_mul_f32_e32 v122, v122, v122
	v_max_f32_e32 v123, 0, v123
	v_max_f32_e32 v124, 0, v129
	v_max_f32_e32 v125, 0, v125
	v_lshl_add_u64 v[146:147], v[156:157], 0, v[158:159]
	v_mul_f32_e32 v126, v126, v126
	v_mul_f32_e32 v123, v123, v123
	v_mul_f32_e32 v124, v124, v124
	v_mul_f32_e32 v125, v125, v125
	v_cvt_pk_bf16_f32 v122, v126, v122
	v_max_f32_e32 v114, 0, v114
	v_cvt_pk_bf16_f32 v123, v123, v124
	v_cvt_pk_bf16_f32 v124, v155, v127
	v_cvt_pk_bf16_f32 v125, v128, v125
	global_store_dwordx4 v[146:147], v[122:125], off nt
	v_max_f32_e32 v115, 0, v115
	v_max_f32_e32 v116, 0, v116
	v_mul_f32_e32 v122, v114, v114
	v_max_f32_e32 v114, 0, v119
	v_mul_f32_e32 v119, v115, v115
	v_max_f32_e32 v115, v120, v120
	v_mul_f32_e32 v120, v116, v116
	v_max_f32_e32 v118, 0, v118
	v_mul_f32_e32 v114, v114, v114
	v_max_f32_e32 v115, 0, v115
	v_max_f32_e32 v116, 0, v121
	v_max_f32_e32 v117, 0, v117
	v_mul_f32_e32 v118, v118, v118
	v_mul_f32_e32 v115, v115, v115
	v_mul_f32_e32 v116, v116, v116
	v_mul_f32_e32 v117, v117, v117
	v_cvt_pk_bf16_f32 v114, v118, v114
	v_cvt_pk_bf16_f32 v115, v115, v116
	v_cvt_pk_bf16_f32 v116, v122, v119
	v_cvt_pk_bf16_f32 v117, v120, v117
	global_store_dwordx4 v[146:147], v[114:117], off offset:256 nt
	s_nop 0
	v_max_f32_e32 v106, 0, v106
	v_or_b32_e32 v114, 16, v154
	v_ashrrev_i32_e32 v115, 31, v114
	v_mul_f32_e32 v116, v106, v106
	v_max_f32_e32 v107, 0, v107
	v_max_f32_e32 v108, 0, v108
	v_lshlrev_b64 v[114:115], 14, v[114:115]
	v_max_f32_e32 v106, 0, v111
	v_mul_f32_e32 v111, v107, v107
	v_max_f32_e32 v107, v112, v112
	v_mul_f32_e32 v112, v108, v108
	v_lshl_add_u64 v[114:115], s[8:9], 0, v[114:115]
	v_max_f32_e32 v110, 0, v110
	v_mul_f32_e32 v106, v106, v106
	v_max_f32_e32 v107, 0, v107
	v_max_f32_e32 v108, 0, v113
	v_max_f32_e32 v109, 0, v109
	v_lshl_add_u64 v[114:115], v[114:115], 0, v[158:159]
	v_mul_f32_e32 v110, v110, v110
	v_mul_f32_e32 v107, v107, v107
	v_mul_f32_e32 v108, v108, v108
	v_mul_f32_e32 v109, v109, v109
	v_cvt_pk_bf16_f32 v106, v110, v106
	v_max_f32_e32 v98, 0, v98
	v_cvt_pk_bf16_f32 v107, v107, v108
	v_cvt_pk_bf16_f32 v108, v116, v111
	v_cvt_pk_bf16_f32 v109, v112, v109
	global_store_dwordx4 v[114:115], v[106:109], off nt
	v_max_f32_e32 v99, 0, v99
	v_max_f32_e32 v100, 0, v100
	v_mul_f32_e32 v106, v98, v98
	v_max_f32_e32 v98, 0, v103
	v_mul_f32_e32 v103, v99, v99
	v_max_f32_e32 v99, v104, v104
	v_mul_f32_e32 v104, v100, v100
	v_max_f32_e32 v102, 0, v102
	v_mul_f32_e32 v98, v98, v98
	v_max_f32_e32 v99, 0, v99
	v_max_f32_e32 v100, 0, v105
	v_max_f32_e32 v101, 0, v101
	v_mul_f32_e32 v102, v102, v102
	v_mul_f32_e32 v99, v99, v99
	v_mul_f32_e32 v100, v100, v100
	v_mul_f32_e32 v101, v101, v101
	v_cvt_pk_bf16_f32 v98, v102, v98
	v_cvt_pk_bf16_f32 v99, v99, v100
	v_cvt_pk_bf16_f32 v100, v106, v103
	v_cvt_pk_bf16_f32 v101, v104, v101
	global_store_dwordx4 v[114:115], v[98:101], off offset:256 nt
	s_nop 0
	v_max_f32_e32 v90, 0, v90
	v_or_b32_e32 v98, 32, v154
	v_ashrrev_i32_e32 v99, 31, v98
	v_mul_f32_e32 v100, v90, v90
	v_max_f32_e32 v91, 0, v91
	v_max_f32_e32 v92, 0, v92
	v_lshlrev_b64 v[98:99], 14, v[98:99]
	v_max_f32_e32 v90, 0, v95
	v_mul_f32_e32 v95, v91, v91
	v_max_f32_e32 v91, v96, v96
	v_mul_f32_e32 v96, v92, v92
	v_lshl_add_u64 v[98:99], s[8:9], 0, v[98:99]
	v_max_f32_e32 v94, 0, v94
	v_mul_f32_e32 v90, v90, v90
	v_max_f32_e32 v91, 0, v91
	v_max_f32_e32 v92, 0, v97
	v_max_f32_e32 v93, 0, v93
	v_lshl_add_u64 v[98:99], v[98:99], 0, v[158:159]
	v_mul_f32_e32 v94, v94, v94
	v_mul_f32_e32 v91, v91, v91
	v_mul_f32_e32 v92, v92, v92
	v_mul_f32_e32 v93, v93, v93
	v_cvt_pk_bf16_f32 v90, v94, v90
	v_max_f32_e32 v82, 0, v82
	v_cvt_pk_bf16_f32 v91, v91, v92
	v_cvt_pk_bf16_f32 v92, v100, v95
	v_cvt_pk_bf16_f32 v93, v96, v93
	global_store_dwordx4 v[98:99], v[90:93], off nt
	v_max_f32_e32 v83, 0, v83
	v_max_f32_e32 v84, 0, v84
	v_mul_f32_e32 v90, v82, v82
	v_max_f32_e32 v82, 0, v87
	v_mul_f32_e32 v87, v83, v83
	v_max_f32_e32 v83, v88, v88
	v_mul_f32_e32 v88, v84, v84
	v_max_f32_e32 v86, 0, v86
	v_mul_f32_e32 v82, v82, v82
	v_max_f32_e32 v83, 0, v83
	v_max_f32_e32 v84, 0, v89
	v_max_f32_e32 v85, 0, v85
	v_mul_f32_e32 v86, v86, v86
	v_mul_f32_e32 v83, v83, v83
	v_mul_f32_e32 v84, v84, v84
	v_mul_f32_e32 v85, v85, v85
	v_cvt_pk_bf16_f32 v82, v86, v82
	v_cvt_pk_bf16_f32 v83, v83, v84
	v_cvt_pk_bf16_f32 v84, v90, v87
	v_cvt_pk_bf16_f32 v85, v88, v85
	global_store_dwordx4 v[98:99], v[82:85], off offset:256 nt
	s_nop 0
	v_max_f32_e32 v74, 0, v74
	v_or_b32_e32 v82, 48, v154
	v_ashrrev_i32_e32 v83, 31, v82
	v_mul_f32_e32 v84, v74, v74
	v_max_f32_e32 v75, 0, v75
	v_max_f32_e32 v76, 0, v76
	v_lshlrev_b64 v[82:83], 14, v[82:83]
	v_max_f32_e32 v74, 0, v79
	v_mul_f32_e32 v79, v75, v75
	v_max_f32_e32 v75, v80, v80
	v_mul_f32_e32 v80, v76, v76
	v_lshl_add_u64 v[82:83], s[8:9], 0, v[82:83]
	v_max_f32_e32 v78, 0, v78
	v_mul_f32_e32 v74, v74, v74
	v_max_f32_e32 v75, 0, v75
	v_max_f32_e32 v76, 0, v81
	v_max_f32_e32 v77, 0, v77
	v_lshl_add_u64 v[82:83], v[82:83], 0, v[158:159]
	v_mul_f32_e32 v78, v78, v78
	v_mul_f32_e32 v75, v75, v75
	v_mul_f32_e32 v76, v76, v76
	v_mul_f32_e32 v77, v77, v77
; template <bool BF> __device__ __forceinline__ unsigned pk2(float lo, float hi) { return BF ? pk_bf2(lo, hi) : pk_h2(lo, hi); }
;     __device__ __forceinline__ void operator()(const f32x4 (&acc)[2][2][4][2], const Unit& u, int wr, int wc, int fr, int fq) const {
;     ...
;             for (int m = 0; m < 4; ++m) { h16* rowp = O + (size_t)(row0 + ai * HALF + m * 16) * ldc + col0;
; #pragma unroll
;                 for (int bj = 0; bj < 2; ++bj) { f32x4 v0 = acc[ai][bj][m][0], v1 = acc[ai][bj][m][1];
;                     if (ACT == 1) {
; #pragma unroll
;                         for (int j = 0; j < 4; ++j) { const float a = fmaxf(v0[j], 0.f), b = fmaxf(v1[j], 0.f); v0[j] = a * a; v1[j] = b * b; } }
;                     u32x4 w; w.x = pk2<BF>(v0[0], v0[1]); w.y = pk2<BF>(v0[2], v0[3]); w.z = pk2<BF>(v1[0], v1[1]); w.w = pk2<BF>(v1[2], v1[3]);
;                     *(u32x4*)(rowp + bj * HALF) = w; } }
	v_cvt_pk_bf16_f32 v74, v78, v74
	v_max_f32_e32 v66, 0, v66
	v_max_f32_e32 v67, 0, v67
	v_max_f32_e32 v68, 0, v68
	v_cvt_pk_bf16_f32 v75, v75, v76
	v_cvt_pk_bf16_f32 v76, v84, v79
	v_cvt_pk_bf16_f32 v77, v80, v77
	global_store_dwordx4 v[82:83], v[74:77], off nt
	s_nop 1
	v_mul_f32_e32 v74, v66, v66
	v_max_f32_e32 v66, v71, v71
	v_mul_f32_e32 v71, v67, v67
	v_max_f32_e32 v67, v72, v72
	v_mul_f32_e32 v72, v68, v68
	v_max_f32_e32 v67, 0, v67
	v_max_f32_e32 v68, 0, v73
	v_max_f32_e32 v66, 0, v66
	v_mul_f32_e32 v67, v67, v67
	v_max_f32_e32 v69, 0, v69
	v_mul_f32_e32 v68, v68, v68
	v_max_f32_e32 v70, 0, v70
	v_mul_f32_e32 v66, v66, v66
	v_mul_f32_e32 v69, v69, v69
	v_cvt_pk_bf16_f32 v67, v67, v68
	v_cvt_pk_bf16_f32 v68, v74, v71
	v_max_f32_e32 v58, 0, v58
	v_mul_f32_e32 v70, v70, v70
	v_cvt_pk_bf16_f32 v66, v70, v66
	v_cvt_pk_bf16_f32 v69, v72, v69
	global_store_dwordx4 v[82:83], v[66:69], off offset:256 nt
	s_nop 0
	v_max_f32_e32 v59, 0, v59
	v_mul_f32_e32 v68, v58, v58
	v_max_f32_e32 v60, 0, v60
	v_max_f32_e32 v62, 0, v62
	v_max_f32_e32 v58, 0, v63
	v_mul_f32_e32 v63, v59, v59
	v_max_f32_e32 v59, v64, v64
	v_mul_f32_e32 v64, v60, v60
	v_mul_f32_e32 v62, v62, v62
	v_mul_f32_e32 v58, v58, v58
	v_max_f32_e32 v59, 0, v59
	v_max_f32_e32 v60, 0, v65
	v_mul_f32_e32 v59, v59, v59
	v_max_f32_e32 v61, 0, v61
	v_mul_f32_e32 v60, v60, v60
	v_cvt_pk_bf16_f32 v58, v62, v58
	v_add_co_u32_e32 v62, vcc, s55, v146
	v_mul_f32_e32 v61, v61, v61
	v_cvt_pk_bf16_f32 v59, v59, v60
	v_cvt_pk_bf16_f32 v60, v68, v63
	v_addc_co_u32_e32 v63, vcc, 0, v147, vcc
	v_max_f32_e32 v50, 0, v50
	v_max_f32_e32 v51, 0, v51
	v_max_f32_e32 v52, 0, v52
	v_cvt_pk_bf16_f32 v61, v64, v61
	global_store_dwordx4 v[62:63], v[58:61], off nt
	s_nop 1
	v_mul_f32_e32 v58, v50, v50
	v_max_f32_e32 v50, v55, v55
	v_mul_f32_e32 v55, v51, v51
	v_max_f32_e32 v51, v56, v56
	v_mul_f32_e32 v56, v52, v52
	v_max_f32_e32 v51, 0, v51
	v_max_f32_e32 v52, 0, v57
	v_max_f32_e32 v50, 0, v50
	v_mul_f32_e32 v51, v51, v51
	v_max_f32_e32 v53, 0, v53
	v_mul_f32_e32 v52, v52, v52
	v_lshl_add_u64 v[66:67], v[146:147], 0, s[16:17]
	v_max_f32_e32 v54, 0, v54
	v_mul_f32_e32 v50, v50, v50
	v_mul_f32_e32 v53, v53, v53
	v_cvt_pk_bf16_f32 v51, v51, v52
	v_cvt_pk_bf16_f32 v52, v58, v55
	v_max_f32_e32 v42, 0, v42
	v_mul_f32_e32 v54, v54, v54
	v_cvt_pk_bf16_f32 v50, v54, v50
	v_cvt_pk_bf16_f32 v53, v56, v53
	global_store_dwordx4 v[66:67], v[50:53], off offset:256 nt
	s_nop 0
	v_max_f32_e32 v43, 0, v43
	v_mul_f32_e32 v52, v42, v42
	v_max_f32_e32 v44, 0, v44
	v_max_f32_e32 v46, 0, v46
	v_max_f32_e32 v42, 0, v47
	v_mul_f32_e32 v47, v43, v43
	v_max_f32_e32 v43, v48, v48
	v_mul_f32_e32 v48, v44, v44
	v_mul_f32_e32 v46, v46, v46
	v_mul_f32_e32 v42, v42, v42
	v_max_f32_e32 v43, 0, v43
	v_max_f32_e32 v44, 0, v49
	v_mul_f32_e32 v43, v43, v43
	v_max_f32_e32 v45, 0, v45
	v_mul_f32_e32 v44, v44, v44
	v_cvt_pk_bf16_f32 v42, v46, v42
	v_add_co_u32_e32 v46, vcc, s56, v146
	v_mul_f32_e32 v45, v45, v45
	v_cvt_pk_bf16_f32 v43, v43, v44
	v_cvt_pk_bf16_f32 v44, v52, v47
	v_addc_co_u32_e32 v47, vcc, 0, v147, vcc
	v_max_f32_e32 v34, 0, v34
	v_max_f32_e32 v35, 0, v35
	v_max_f32_e32 v36, 0, v36
	v_cvt_pk_bf16_f32 v45, v48, v45
	global_store_dwordx4 v[46:47], v[42:45], off nt
	s_nop 1
	v_mul_f32_e32 v42, v34, v34
	v_max_f32_e32 v34, v39, v39
	v_mul_f32_e32 v39, v35, v35
	v_max_f32_e32 v35, v40, v40
	v_mul_f32_e32 v40, v36, v36
	v_max_f32_e32 v35, 0, v35
	v_max_f32_e32 v36, 0, v41
	v_max_f32_e32 v34, 0, v34
	v_mul_f32_e32 v35, v35, v35
	v_max_f32_e32 v37, 0, v37
	v_mul_f32_e32 v36, v36, v36
	v_lshl_add_u64 v[50:51], v[146:147], 0, s[18:19]
	v_max_f32_e32 v38, 0, v38
	v_mul_f32_e32 v34, v34, v34
	v_mul_f32_e32 v37, v37, v37
	v_cvt_pk_bf16_f32 v35, v35, v36
	v_cvt_pk_bf16_f32 v36, v42, v39
	v_max_f32_e32 v26, 0, v26
	v_mul_f32_e32 v38, v38, v38
	v_cvt_pk_bf16_f32 v34, v38, v34
	v_cvt_pk_bf16_f32 v37, v40, v37
	global_store_dwordx4 v[50:51], v[34:37], off offset:256 nt
	s_nop 0
	v_max_f32_e32 v27, 0, v27
	v_mul_f32_e32 v36, v26, v26
	v_max_f32_e32 v28, 0, v28
	v_max_f32_e32 v30, 0, v30
	v_max_f32_e32 v26, 0, v31
	v_mul_f32_e32 v31, v27, v27
	v_max_f32_e32 v27, v32, v32
	v_mul_f32_e32 v32, v28, v28
	v_mul_f32_e32 v30, v30, v30
	v_mul_f32_e32 v26, v26, v26
	v_max_f32_e32 v27, 0, v27
	v_max_f32_e32 v28, 0, v33
	v_mul_f32_e32 v27, v27, v27
	v_max_f32_e32 v29, 0, v29
	v_mul_f32_e32 v28, v28, v28
	v_cvt_pk_bf16_f32 v26, v30, v26
	v_add_co_u32_e32 v30, vcc, s57, v146
	v_mul_f32_e32 v29, v29, v29
	v_cvt_pk_bf16_f32 v27, v27, v28
	v_cvt_pk_bf16_f32 v28, v36, v31
	v_addc_co_u32_e32 v31, vcc, 0, v147, vcc
	v_max_f32_e32 v18, 0, v18
	v_max_f32_e32 v19, 0, v19
	v_max_f32_e32 v20, 0, v20
	v_cvt_pk_bf16_f32 v29, v32, v29
	global_store_dwordx4 v[30:31], v[26:29], off nt
	s_nop 1
	v_mul_f32_e32 v26, v18, v18
	v_max_f32_e32 v18, v23, v23
	v_mul_f32_e32 v23, v19, v19
	v_max_f32_e32 v19, v24, v24
	v_mul_f32_e32 v24, v20, v20
	v_max_f32_e32 v19, 0, v19
	v_max_f32_e32 v20, 0, v25
	v_max_f32_e32 v18, 0, v18
	v_mul_f32_e32 v19, v19, v19
	v_max_f32_e32 v21, 0, v21
	v_mul_f32_e32 v20, v20, v20
	v_lshl_add_u64 v[34:35], v[146:147], 0, s[20:21]
	v_max_f32_e32 v22, 0, v22
	v_mul_f32_e32 v18, v18, v18
	v_mul_f32_e32 v21, v21, v21
	v_cvt_pk_bf16_f32 v19, v19, v20
	v_cvt_pk_bf16_f32 v20, v26, v23
	v_max_f32_e32 v10, 0, v10
	v_mul_f32_e32 v22, v22, v22
	v_cvt_pk_bf16_f32 v18, v22, v18
	v_cvt_pk_bf16_f32 v21, v24, v21
	global_store_dwordx4 v[34:35], v[18:21], off offset:256 nt
	s_nop 0
	v_max_f32_e32 v11, 0, v11
	v_mul_f32_e32 v20, v10, v10
	v_max_f32_e32 v12, 0, v12
	v_max_f32_e32 v14, 0, v14
	v_max_f32_e32 v10, 0, v15
	v_mul_f32_e32 v15, v11, v11
	v_max_f32_e32 v11, v16, v16
	v_mul_f32_e32 v16, v12, v12
	v_mul_f32_e32 v14, v14, v14
	v_mul_f32_e32 v10, v10, v10
	v_max_f32_e32 v11, 0, v11
	v_max_f32_e32 v12, 0, v17
	v_mul_f32_e32 v11, v11, v11
	v_max_f32_e32 v13, 0, v13
	v_mul_f32_e32 v12, v12, v12
	v_cvt_pk_bf16_f32 v10, v14, v10
	v_add_co_u32_e32 v14, vcc, s58, v146
	v_mul_f32_e32 v13, v13, v13
	v_cvt_pk_bf16_f32 v11, v11, v12
	v_cvt_pk_bf16_f32 v12, v20, v15
	v_addc_co_u32_e32 v15, vcc, 0, v147, vcc
	v_max_f32_e32 v2, 0, v2
	v_max_f32_e32 v3, 0, v3
	v_max_f32_e32 v4, 0, v4
	v_cvt_pk_bf16_f32 v13, v16, v13
	global_store_dwordx4 v[14:15], v[10:13], off nt
	s_nop 1
	v_mul_f32_e32 v10, v2, v2
	v_max_f32_e32 v2, v7, v7
	v_mul_f32_e32 v7, v3, v3
	v_max_f32_e32 v3, v8, v8
	v_mul_f32_e32 v8, v4, v4
	v_max_f32_e32 v2, 0, v2
	v_max_f32_e32 v3, 0, v3
	v_max_f32_e32 v4, 0, v9
	v_max_f32_e32 v5, 0, v5
	v_lshl_add_u64 v[18:19], v[146:147], 0, s[22:23]
	v_max_f32_e32 v6, 0, v6
	v_mul_f32_e32 v2, v2, v2
	v_mul_f32_e32 v3, v3, v3
	v_mul_f32_e32 v4, v4, v4
	v_mul_f32_e32 v5, v5, v5
	s_andn2_b64 vcc, exec, s[4:5]
	s_mov_b64 s[4:5], -1
	v_mul_f32_e32 v6, v6, v6
	v_cvt_pk_bf16_f32 v2, v6, v2
	v_cvt_pk_bf16_f32 v3, v3, v4
	v_cvt_pk_bf16_f32 v4, v10, v7
	v_cvt_pk_bf16_f32 v5, v8, v5
	global_store_dwordx4 v[18:19], v[2:5], off offset:256 nt
	s_cbranch_vccnz .LBB0_861
	s_andn2_b64 vcc, exec, s[6:7]
	s_cbranch_vccnz .LBB0_860
	s_barrier
	s_branch .LBB0_860
